# mLSTM chunk-state phase (m_dc): all 16 K-fragment loads of a unit issued with its V/gate loads; vmcnt waits re-derived
# speedup vs baseline: 1.1331x; 1.1331x over previous
; DI unsigned pk2(float lo, float hi) { f32x2 v = {lo, hi}; bf16x2_t b = __builtin_convertvector(v, bf16x2_t); return __builtin_bit_cast(unsigned, b); }
; DI float bflo(unsigned u) { return __uint_as_float(u << 16); }
; DI float bfhi(unsigned u) { return __uint_as_float(u & 0xffff0000u); }
; DI float fexp(float x) { return __builtin_amdgcn_exp2f(x * LOG2E); }
; DI void phase_m_dc(int wv, const ArgP a) {
;     ...
;     for (int u = blockIdx.x; u < 1024; u += gridDim.x) {
;         const int c = u >> 2, h = u & 3; const size_t t0 = (size_t)c * 64;
;         const float emax = ML[c * 4 + h] - BL[c * 4 + h];
;         bf16x8 bfr[4];
;         { const bf16_t* vp = KVT + (size_t)(512 + h * 256 + 32 * w + r32) * S + t0 + 8 * hi; const float* gp = GE + (size_t)h * S + t0 + 8 * hi;
; #pragma unroll
;           for (int ks = 0; ks < 4; ++ks) { const u32x4 v = *(const u32x4*)(vp + 16 * ks); const f32x4 e0 = *(const f32x4*)(gp + 16 * ks), e1 = *(const f32x4*)(gp + 16 * ks + 4);
;               u32x4 o; o.x = pk2(bflo(v.x) * fexp(e0[0] - emax), bfhi(v.x) * fexp(e0[1] - emax)); o.y = pk2(bflo(v.y) * fexp(e0[2] - emax), bfhi(v.y) * fexp(e0[3] - emax));
;               o.z = pk2(bflo(v.z) * fexp(e1[0] - emax), bfhi(v.z) * fexp(e1[1] - emax)); o.w = pk2(bflo(v.w) * fexp(e1[2] - emax), bfhi(v.w) * fexp(e1[3] - emax));
;               bfr[ks] = __builtin_bit_cast(bf16x8, o); } }
;         const bf16_t* kp = KVT + (size_t)(h * 128 + r32) * S + t0 + 8 * hi;
;         bf16_t* op = CST + ((size_t)(c * 4 + h) * 256 + 32 * w + r32) * 128 + 8 * hi;
; #pragma unroll
;         for (int rb = 0; rb < 4; ++rb) { f32x16 acc = {};
; #pragma unroll
;             for (int ks = 0; ks < 4; ++ks) { const bf16x8 ka = *(const bf16x8*)(kp + (size_t)(32 * rb) * S + 16 * ks); acc = __builtin_amdgcn_mfma_f32_32x32x16_bf16(ka, bfr[ks], acc, 0, 0, 0); }
; #pragma unroll
;             for (int p = 0; p < 2; ++p) {
;                 const unsigned a0 = pk2(acc[8 * p], acc[8 * p + 1]), a1 = pk2(acc[8 * p + 2], acc[8 * p + 3]), b0 = pk2(acc[8 * p + 4], acc[8 * p + 5]), b1 = pk2(acc[8 * p + 6], acc[8 * p + 7]);
;                 const auto r0 = __builtin_amdgcn_permlane32_swap(a0, b0, false, false), r1 = __builtin_amdgcn_permlane32_swap(a1, b1, false, false);
;                 *(u32x4*)(op + 32 * rb + 16 * p) = (u32x4){r0[0], r1[0], r0[1], r1[1]}; } }
.LBB0_1463:
	s_ashr_i32 s10, s2, 2
	s_ashr_i32 s3, s2, 31
	s_and_b32 s22, s2, 3
	s_ashr_i32 s11, s10, 31
	s_lshl_b64 s[4:5], s[2:3], 2
	s_add_u32 s8, s14, s4
	s_addc_u32 s9, s15, s5
	s_add_u32 s4, s12, s4
	s_addc_u32 s5, s13, s5
	global_load_dword v32, v33, s[8:9]
	global_load_dword v40, v33, s[4:5]
	v_lshl_add_u32 v0, s22, 8, v49
	v_ashrrev_i32_e32 v1, 31, v0
	v_lshlrev_b64 v[0:1], 15, v[0:1]
	v_lshl_add_u64 v[0:1], s[0:1], 0, v[0:1]
	s_lshl_b64 s[4:5], s[10:11], 7
	s_lshl_b32 s8, s22, 16
	v_lshl_add_u64 v[0:1], v[0:1], 0, s[4:5]
	s_add_u32 s23, s16, s8
	v_lshl_add_u64 v[12:13], v[0:1], 0, v[38:39]
	s_addc_u32 s24, s17, 0
	s_lshl_b64 s[8:9], s[10:11], 8
	global_load_dwordx4 v[18:21], v[12:13], off
	global_load_dwordx4 v[0:3], v[12:13], off offset:32
	s_add_u32 s8, s23, s8
	s_addc_u32 s9, s24, s9
	global_load_dwordx4 v[22:25], v31, s[8:9]
	global_load_dwordx4 v[26:29], v31, s[8:9] offset:16
	global_load_dwordx4 v[52:55], v31, s[8:9] offset:64
	global_load_dwordx4 v[8:11], v31, s[8:9] offset:80
	global_load_dwordx4 v[4:7], v[12:13], off offset:64
	global_load_dwordx4 v[14:17], v[12:13], off offset:96
	global_load_dwordx4 v[56:59], v31, s[8:9] offset:144
	global_load_dwordx4 v[60:63], v31, s[8:9] offset:128
	global_load_dwordx4 v[64:67], v31, s[8:9] offset:208
	global_load_dwordx4 v[68:71], v31, s[8:9] offset:192
	s_lshl_b32 s22, s22, 7
	v_or_b32_e32 v116, s22, v48
	v_mov_b32_e32 v117, 0
	v_lshlrev_b32_e32 v116, 15, v116
	v_lshl_add_u64 v[118:119], s[0:1], 0, v[116:117]
	v_lshl_add_u64 v[118:119], v[118:119], 0, s[4:5]
	v_lshl_add_u64 v[120:121], v[118:119], 0, v[38:39]
	global_load_dwordx4 v[100:103], v[120:121], off
	global_load_dwordx4 v[104:107], v[120:121], off offset:32
	global_load_dwordx4 v[108:111], v[120:121], off offset:64
	global_load_dwordx4 v[112:115], v[120:121], off offset:96
	v_add_co_u32_e64 v122, s[26:27], s19, v120
	s_nop 1
	v_addc_co_u32_e64 v123, s[26:27], 0, v121, s[26:27]
	global_load_dwordx4 v[140:143], v[122:123], off
	global_load_dwordx4 v[144:147], v[122:123], off offset:32
	global_load_dwordx4 v[148:151], v[122:123], off offset:64
	global_load_dwordx4 v[152:155], v[122:123], off offset:96
	v_add_co_u32_e64 v122, s[26:27], s20, v120
	s_nop 1
	v_addc_co_u32_e64 v123, s[26:27], 0, v121, s[26:27]
	global_load_dwordx4 v[156:159], v[122:123], off
	global_load_dwordx4 v[160:163], v[122:123], off offset:32
	global_load_dwordx4 v[164:167], v[122:123], off offset:64
	global_load_dwordx4 v[168:171], v[122:123], off offset:96
	v_add_co_u32_e64 v122, s[26:27], s21, v120
	s_nop 1
	v_addc_co_u32_e64 v123, s[26:27], 0, v121, s[26:27]
	global_load_dwordx4 v[172:175], v[122:123], off
	global_load_dwordx4 v[176:179], v[122:123], off offset:32
	global_load_dwordx4 v[180:183], v[122:123], off offset:64
	global_load_dwordx4 v[184:187], v[122:123], off offset:96
	s_waitcnt vmcnt(28)
	v_sub_f32_e32 v50, v32, v40
	s_waitcnt vmcnt(25)
	v_sub_f32_e32 v24, v24, v50
	v_sub_f32_e32 v25, v25, v50
	s_waitcnt vmcnt(23)
	v_sub_f32_e32 v32, v52, v50
	v_sub_f32_e32 v51, v53, v50
	v_sub_f32_e32 v52, v54, v50
	v_sub_f32_e32 v53, v55, v50
	v_sub_f32_e32 v22, v22, v50
	v_sub_f32_e32 v23, v23, v50
	v_mul_f32_e32 v24, 0x3fb8aa3b, v24
	v_mul_f32_e32 v25, 0x3fb8aa3b, v25
	v_mul_f32_e32 v54, 0x3fb8aa3b, v52
	v_mul_f32_e32 v55, 0x3fb8aa3b, v53
	v_mul_f32_e32 v22, 0x3fb8aa3b, v22
	v_mul_f32_e32 v23, 0x3fb8aa3b, v23
	v_exp_f32_e32 v24, v24
	v_exp_f32_e32 v25, v25
	v_exp_f32_e32 v54, v54
	v_exp_f32_e32 v55, v55
	v_exp_f32_e32 v22, v22
	v_exp_f32_e32 v23, v23
	v_lshlrev_b32_e32 v12, 16, v18
	v_and_b32_e32 v13, 0xffff0000, v18
	v_lshlrev_b32_e32 v18, 16, v19
	v_and_b32_e32 v19, 0xffff0000, v19
	v_lshlrev_b32_e32 v72, 16, v0
	v_and_b32_e32 v73, 0xffff0000, v0
	v_lshlrev_b32_e32 v0, 16, v1
	v_and_b32_e32 v1, 0xffff0000, v1
	v_sub_f32_e32 v26, v26, v50
	v_sub_f32_e32 v27, v27, v50
	v_mul_f32_e32 v26, 0x3fb8aa3b, v26
	v_mul_f32_e32 v27, 0x3fb8aa3b, v27
	v_pk_mul_f32 v[18:19], v[24:25], v[18:19]
	v_pk_mul_f32 v[0:1], v[54:55], v[0:1]
	v_mul_f32_e32 v32, 0x3fb8aa3b, v32
	v_mul_f32_e32 v51, 0x3fb8aa3b, v51
	v_exp_f32_e32 v26, v26
	v_exp_f32_e32 v27, v27
	v_pk_mul_f32 v[12:13], v[22:23], v[12:13]
	v_cvt_pk_bf16_f32 v23, v18, v19
	v_cvt_pk_bf16_f32 v19, v0, v1
	v_or_b32_e32 v0, s22, v48
	v_exp_f32_e32 v52, v32
	v_exp_f32_e32 v53, v51
	v_lshlrev_b32_e32 v32, 15, v0
	v_lshl_add_u64 v[0:1], s[0:1], 0, v[32:33]
	v_lshlrev_b32_e32 v40, 16, v20
	v_and_b32_e32 v41, 0xffff0000, v20
	v_lshl_add_u64 v[0:1], v[0:1], 0, s[4:5]
	v_pk_mul_f32 v[24:25], v[26:27], v[40:41]
	v_lshl_add_u64 v[40:41], v[0:1], 0, v[38:39]
	v_pk_mul_f32 v[26:27], v[52:53], v[72:73]
	s_waitcnt vmcnt(22)
	v_sub_f32_e32 v8, v8, v50
	v_sub_f32_e32 v1, v9, v50
	v_sub_f32_e32 v28, v28, v50
	v_sub_f32_e32 v29, v29, v50
	v_mul_f32_e32 v0, 0x3fb8aa3b, v8
	v_mul_f32_e32 v1, 0x3fb8aa3b, v1
	v_mul_f32_e32 v28, 0x3fb8aa3b, v28
	v_mul_f32_e32 v29, 0x3fb8aa3b, v29
	v_exp_f32_e32 v0, v0
	v_exp_f32_e32 v1, v1
	v_exp_f32_e32 v28, v28
	v_exp_f32_e32 v29, v29
	v_lshlrev_b32_e32 v8, 16, v2
	v_and_b32_e32 v9, 0xffff0000, v2
	v_sub_f32_e32 v2, v10, v50
	v_mul_f32_e32 v2, 0x3fb8aa3b, v2
	v_lshlrev_b32_e32 v20, 16, v21
	v_and_b32_e32 v21, 0xffff0000, v21
	v_pk_mul_f32 v[0:1], v[0:1], v[8:9]
	v_exp_f32_e32 v8, v2
	v_sub_f32_e32 v2, v11, v50
	v_pk_mul_f32 v[20:21], v[28:29], v[20:21]
	v_mul_f32_e32 v2, 0x3fb8aa3b, v2
	v_cvt_pk_bf16_f32 v24, v24, v25
	v_cvt_pk_bf16_f32 v25, v20, v21
	v_exp_f32_e32 v9, v2
	v_cvt_pk_bf16_f32 v20, v0, v1
	v_lshlrev_b32_e32 v0, 16, v3
	v_and_b32_e32 v1, 0xffff0000, v3
	s_waitcnt vmcnt(18)
; DI unsigned pk2(float lo, float hi) { f32x2 v = {lo, hi}; bf16x2_t b = __builtin_convertvector(v, bf16x2_t); return __builtin_bit_cast(unsigned, b); }
; DI void phase_m_dc(int wv, const ArgP a) {
;     ...
;         const bf16_t* kp = KVT + (size_t)(h * 128 + r32) * S + t0 + 8 * hi;
;         bf16_t* op = CST + ((size_t)(c * 4 + h) * 256 + 32 * w + r32) * 128 + 8 * hi;
; #pragma unroll
;         for (int rb = 0; rb < 4; ++rb) { f32x16 acc = {};
; #pragma unroll
;             for (int ks = 0; ks < 4; ++ks) { const bf16x8 ka = *(const bf16x8*)(kp + (size_t)(32 * rb) * S + 16 * ks); acc = __builtin_amdgcn_mfma_f32_32x32x16_bf16(ka, bfr[ks], acc, 0, 0, 0); }
; #pragma unroll
;             for (int p = 0; p < 2; ++p) {
;                 const unsigned a0 = pk2(acc[8 * p], acc[8 * p + 1]), a1 = pk2(acc[8 * p + 2], acc[8 * p + 3]), b0 = pk2(acc[8 * p + 4], acc[8 * p + 5]), b1 = pk2(acc[8 * p + 6], acc[8 * p + 7]);
;                 const auto r0 = __builtin_amdgcn_permlane32_swap(a0, b0, false, false), r1 = __builtin_amdgcn_permlane32_swap(a1, b1, false, false);
;                 *(u32x4*)(op + 32 * rb + 16 * p) = (u32x4){r0[0], r1[0], r0[1], r1[1]}; } }
	v_sub_f32_e32 v2, v60, v50
	v_sub_f32_e32 v3, v61, v50
	v_mul_f32_e32 v2, 0x3fb8aa3b, v2
	v_mul_f32_e32 v3, 0x3fb8aa3b, v3
	v_exp_f32_e32 v2, v2
	v_exp_f32_e32 v3, v3
	v_pk_mul_f32 v[0:1], v[8:9], v[0:1]
	v_cvt_pk_bf16_f32 v18, v26, v27
	v_cvt_pk_bf16_f32 v21, v0, v1
	v_lshlrev_b32_e32 v0, 16, v4
	v_and_b32_e32 v1, 0xffff0000, v4
	v_pk_mul_f32 v[0:1], v[2:3], v[0:1]
	v_sub_f32_e32 v2, v62, v50
	v_sub_f32_e32 v3, v63, v50
	v_mul_f32_e32 v2, 0x3fb8aa3b, v2
	v_mul_f32_e32 v3, 0x3fb8aa3b, v3
	v_exp_f32_e32 v2, v2
	v_exp_f32_e32 v3, v3
	v_cvt_pk_bf16_f32 v26, v0, v1
	v_lshlrev_b32_e32 v0, 16, v5
	v_and_b32_e32 v1, 0xffff0000, v5
	v_pk_mul_f32 v[0:1], v[2:3], v[0:1]
	v_sub_f32_e32 v2, v56, v50
	v_sub_f32_e32 v3, v57, v50
	v_mul_f32_e32 v2, 0x3fb8aa3b, v2
	v_mul_f32_e32 v3, 0x3fb8aa3b, v3
	v_exp_f32_e32 v2, v2
	v_exp_f32_e32 v3, v3
	v_cvt_pk_bf16_f32 v27, v0, v1
	v_lshlrev_b32_e32 v0, 16, v6
	v_and_b32_e32 v1, 0xffff0000, v6
	v_pk_mul_f32 v[0:1], v[2:3], v[0:1]
	v_sub_f32_e32 v2, v58, v50
	v_sub_f32_e32 v3, v59, v50
	v_mul_f32_e32 v2, 0x3fb8aa3b, v2
	v_mul_f32_e32 v3, 0x3fb8aa3b, v3
	v_exp_f32_e32 v2, v2
	v_exp_f32_e32 v3, v3
	v_cvt_pk_bf16_f32 v28, v0, v1
	v_lshlrev_b32_e32 v0, 16, v7
	v_and_b32_e32 v1, 0xffff0000, v7
	v_pk_mul_f32 v[0:1], v[2:3], v[0:1]
	s_waitcnt vmcnt(16)
	v_sub_f32_e32 v2, v68, v50
	v_sub_f32_e32 v3, v69, v50
	v_mul_f32_e32 v2, 0x3fb8aa3b, v2
	v_mul_f32_e32 v3, 0x3fb8aa3b, v3
	v_exp_f32_e32 v2, v2
	v_exp_f32_e32 v3, v3
	v_cvt_pk_bf16_f32 v29, v0, v1
	v_lshlrev_b32_e32 v0, 16, v14
	v_and_b32_e32 v1, 0xffff0000, v14
	v_pk_mul_f32 v[0:1], v[2:3], v[0:1]
	v_sub_f32_e32 v2, v70, v50
	v_sub_f32_e32 v3, v71, v50
	v_mul_f32_e32 v2, 0x3fb8aa3b, v2
	v_mul_f32_e32 v3, 0x3fb8aa3b, v3
	v_exp_f32_e32 v2, v2
	v_exp_f32_e32 v3, v3
	v_cvt_pk_bf16_f32 v56, v0, v1
	v_lshlrev_b32_e32 v0, 16, v15
	v_and_b32_e32 v1, 0xffff0000, v15
	v_cvt_pk_bf16_f32 v22, v12, v13
	v_pk_mul_f32 v[0:1], v[2:3], v[0:1]
	v_sub_f32_e32 v32, v64, v50
	v_cvt_pk_bf16_f32 v57, v0, v1
	s_waitcnt vmcnt(15)
	v_mfma_f32_32x32x16_bf16 v[0:15], v[100:103], v[22:25], 0
	v_mul_f32_e32 v32, 0x3fb8aa3b, v32
	v_exp_f32_e32 v52, v32
	v_sub_f32_e32 v32, v65, v50
	v_mul_f32_e32 v32, 0x3fb8aa3b, v32
	v_exp_f32_e32 v53, v32
	v_lshlrev_b32_e32 v54, 16, v16
	v_and_b32_e32 v55, 0xffff0000, v16
	s_waitcnt vmcnt(14)
	v_mfma_f32_32x32x16_bf16 v[0:15], v[104:107], v[18:21], v[0:15]
	v_sub_f32_e32 v16, v66, v50
	v_mul_f32_e32 v16, 0x3fb8aa3b, v16
	v_mul_f32_e64 v52, v52, v54
	v_mul_f32_e64 v53, v53, v55
	v_exp_f32_e32 v54, v16
	v_sub_f32_e32 v16, v67, v50
	v_mul_f32_e32 v16, 0x3fb8aa3b, v16
	v_exp_f32_e32 v55, v16
	s_waitcnt vmcnt(13)
	v_mfma_f32_32x32x16_bf16 v[0:15], v[108:111], v[26:29], v[0:15]
	v_lshlrev_b32_e32 v16, 16, v17
	v_and_b32_e32 v17, 0xffff0000, v17
	v_mul_f32_e64 v16, v54, v16
	v_mul_f32_e64 v17, v55, v17
	v_cvt_pk_bf16_f32 v58, v52, v53
	v_cvt_pk_bf16_f32 v59, v16, v17
	s_lshl_b64 s[4:5], s[2:3], 16
	v_lshl_add_u64 v[68:69], v[36:37], 0, s[4:5]
	s_waitcnt vmcnt(12)
	v_mfma_f32_32x32x16_bf16 v[0:15], v[112:115], v[56:59], v[0:15]
	v_add_co_u32_e64 v64, s[4:5], s19, v40
	s_nop 1
	v_addc_co_u32_e64 v65, s[4:5], 0, v41, s[4:5]
	v_add_co_u32_e64 v70, s[4:5], s20, v40
	s_nop 6
	v_cvt_pk_bf16_f32 v0, v0, v1
	v_cvt_pk_bf16_f32 v1, v2, v3
	v_cvt_pk_bf16_f32 v2, v4, v5
	v_cvt_pk_bf16_f32 v3, v6, v7
	s_nop 0
	v_permlane32_swap_b32_e32 v0, v2
	v_permlane32_swap_b32_e32 v1, v3
	global_store_dwordx4 v[68:69], v[0:3], off
	v_cvt_pk_bf16_f32 v4, v8, v9
	v_cvt_pk_bf16_f32 v5, v10, v11
	v_cvt_pk_bf16_f32 v6, v12, v13
	v_cvt_pk_bf16_f32 v7, v14, v15
	s_nop 0
	v_permlane32_swap_b32_e32 v4, v6
	v_permlane32_swap_b32_e32 v5, v7
	global_store_dwordx4 v[68:69], v[4:7], off offset:32
	v_addc_co_u32_e64 v71, s[4:5], 0, v41, s[4:5]
	s_waitcnt vmcnt(13)
	v_mfma_f32_32x32x16_bf16 v[2:17], v[140:143], v[22:25], 0
	s_waitcnt vmcnt(12)
	v_mfma_f32_32x32x16_bf16 v[2:17], v[144:147], v[18:21], v[2:17]
	s_waitcnt vmcnt(11)
	v_mfma_f32_32x32x16_bf16 v[2:17], v[148:151], v[26:29], v[2:17]
	s_waitcnt vmcnt(10)
	v_mfma_f32_32x32x16_bf16 v[2:17], v[152:155], v[56:59], v[2:17]
	s_nop 11
	v_cvt_pk_bf16_f32 v0, v2, v3
	v_cvt_pk_bf16_f32 v1, v4, v5
	v_cvt_pk_bf16_f32 v2, v6, v7
	v_cvt_pk_bf16_f32 v3, v8, v9
	s_nop 0
	v_permlane32_swap_b32_e32 v0, v2
	v_permlane32_swap_b32_e32 v1, v3
	global_store_dwordx4 v[68:69], v[0:3], off offset:64
	v_cvt_pk_bf16_f32 v64, v10, v11
	v_cvt_pk_bf16_f32 v65, v12, v13
	v_cvt_pk_bf16_f32 v66, v14, v15
	s_waitcnt vmcnt(10)
	v_mfma_f32_32x32x16_bf16 v[0:15], v[156:159], v[22:25], 0
	v_cvt_pk_bf16_f32 v67, v16, v17
	v_permlane32_swap_b32_e32 v64, v66
	s_nop 0
	v_permlane32_swap_b32_e32 v65, v67
	global_store_dwordx4 v[68:69], v[64:67], off offset:96
	s_waitcnt vmcnt(10)
	v_mfma_f32_32x32x16_bf16 v[0:15], v[160:163], v[18:21], v[0:15]
	v_add_co_u32_e64 v16, s[4:5], s21, v40
	s_nop 1
	v_addc_co_u32_e64 v17, s[4:5], 0, v41, s[4:5]
	s_waitcnt vmcnt(9)
	v_mfma_f32_32x32x16_bf16 v[0:15], v[164:167], v[26:29], v[0:15]
	s_waitcnt vmcnt(8)
	v_mfma_f32_32x32x16_bf16 v[0:15], v[168:171], v[56:59], v[0:15]
	s_nop 11
	v_cvt_pk_bf16_f32 v0, v0, v1
	v_cvt_pk_bf16_f32 v1, v2, v3
	v_cvt_pk_bf16_f32 v2, v4, v5
	v_cvt_pk_bf16_f32 v3, v6, v7
	s_nop 0
	v_permlane32_swap_b32_e32 v0, v2
	v_permlane32_swap_b32_e32 v1, v3
	global_store_dwordx4 v[68:69], v[0:3], off offset:128
	v_cvt_pk_bf16_f32 v4, v8, v9
	v_cvt_pk_bf16_f32 v5, v10, v11
	v_cvt_pk_bf16_f32 v6, v12, v13
	v_cvt_pk_bf16_f32 v7, v14, v15
	s_nop 0
	v_permlane32_swap_b32_e32 v4, v6
	v_permlane32_swap_b32_e32 v5, v7
	global_store_dwordx4 v[68:69], v[4:7], off offset:160
	s_waitcnt vmcnt(9)
	v_mfma_f32_32x32x16_bf16 v[0:15], v[172:175], v[22:25], 0
	s_waitcnt vmcnt(8)
	v_mfma_f32_32x32x16_bf16 v[0:15], v[176:179], v[18:21], v[0:15]
	s_waitcnt vmcnt(7)
	v_mfma_f32_32x32x16_bf16 v[0:15], v[180:183], v[26:29], v[0:15]
	s_waitcnt vmcnt(6)
	v_mfma_f32_32x32x16_bf16 v[0:15], v[184:187], v[56:59], v[0:15]
	s_nop 11
	v_cvt_pk_bf16_f32 v0, v0, v1
	v_cvt_pk_bf16_f32 v1, v2, v3
	v_cvt_pk_bf16_f32 v2, v4, v5
	v_cvt_pk_bf16_f32 v3, v6, v7
	v_cvt_pk_bf16_f32 v4, v8, v9
	v_cvt_pk_bf16_f32 v5, v10, v11
	v_cvt_pk_bf16_f32 v6, v12, v13
	v_cvt_pk_bf16_f32 v7, v14, v15
	v_permlane32_swap_b32_e32 v0, v2
	v_permlane32_swap_b32_e32 v1, v3
	v_permlane32_swap_b32_e32 v4, v6
	v_permlane32_swap_b32_e32 v5, v7
	global_store_dwordx4 v[68:69], v[0:3], off offset:192
	global_store_dwordx4 v[68:69], v[4:7], off offset:224
	s_and_saveexec_b64 s[4:5], vcc
	s_cbranch_execz .LBB0_1462
; DI float bflo(unsigned u) { return __uint_as_float(u << 16); }
; DI float bfhi(unsigned u) { return __uint_as_float(u & 0xffff0000u); }
; DI float fexp(float x) { return __builtin_amdgcn_exp2f(x * LOG2E); }
; DI void phase_m_dc(int wv, const ArgP a) {
;     ...
;         if (tid < 128) { const bf16_t* kr = KVT + (size_t)(h * 128 + tid) * S + t0; const float* gp = GE + (size_t)h * S + t0; float s = 0.f;
; #pragma unroll
;             for (int p = 0; p < 8; ++p) { const u32x4 v = *(const u32x4*)(kr + 8 * p); const f32x4 e0 = *(const f32x4*)(gp + 8 * p), e1 = *(const f32x4*)(gp + 8 * p + 4);
;                 s += bflo(v.x) * fexp(e0[0] - emax) + bfhi(v.x) * fexp(e0[1] - emax) + bflo(v.y) * fexp(e0[2] - emax) + bfhi(v.y) * fexp(e0[3] - emax)
;                    + bflo(v.z) * fexp(e1[0] - emax) + bfhi(v.z) * fexp(e1[1] - emax) + bflo(v.w) * fexp(e1[2] - emax) + bfhi(v.w) * fexp(e1[3] - emax); }
;             NST[(size_t)(c * 4 + h) * 128 + tid] = s; }
	global_load_dwordx4 v[10:13], v33, s[8:9]
	global_load_dwordx4 v[14:17], v33, s[8:9] offset:16
	global_load_dwordx4 v[18:21], v33, s[8:9] offset:32
	global_load_dwordx4 v[22:25], v33, s[8:9] offset:48
	global_load_dwordx4 v[26:29], v33, s[8:9] offset:64
	v_add_u32_e32 v0, s22, v30
	v_ashrrev_i32_e32 v1, 31, v0
	v_lshlrev_b64 v[0:1], 15, v[0:1]
	s_lshl_b64 s[10:11], s[10:11], 6
	v_lshl_add_u64 v[0:1], s[0:1], 0, v[0:1]
	v_lshl_add_u64 v[8:9], s[10:11], 1, v[0:1]
	global_load_dwordx4 v[52:55], v[8:9], off offset:16
	global_load_dwordx4 v[56:59], v[8:9], off
	global_load_dwordx4 v[60:63], v33, s[8:9] offset:80
	global_load_dwordx4 v[64:67], v33, s[8:9] offset:112
	global_load_dwordx4 v[68:71], v33, s[8:9] offset:96
	global_load_dwordx4 v[0:3], v[8:9], off offset:32
	global_load_dwordx4 v[4:7], v[8:9], off offset:48
	s_waitcnt vmcnt(11)
	v_sub_f32_e32 v11, v11, v50
	v_sub_f32_e32 v13, v13, v50
	s_waitcnt vmcnt(9)
	v_sub_f32_e32 v19, v19, v50
	v_sub_f32_e32 v10, v10, v50
	v_sub_f32_e32 v12, v12, v50
	v_sub_f32_e32 v16, v16, v50
	v_sub_f32_e32 v18, v18, v50
	v_mul_f32_e32 v11, 0x3fb8aa3b, v11
	v_mul_f32_e32 v13, 0x3fb8aa3b, v13
	v_mul_f32_e32 v19, 0x3fb8aa3b, v19
	v_sub_f32_e32 v15, v15, v50
	v_sub_f32_e32 v20, v20, v50
	v_mul_f32_e32 v10, 0x3fb8aa3b, v10
	v_mul_f32_e32 v32, 0x3fb8aa3b, v12
	v_mul_f32_e32 v41, 0x3fb8aa3b, v16
	v_mul_f32_e32 v51, 0x3fb8aa3b, v18
	v_exp_f32_e32 v12, v11
	v_exp_f32_e32 v16, v13
	v_exp_f32_e32 v13, v19
	v_sub_f32_e32 v14, v14, v50
	v_sub_f32_e32 v17, v17, v50
	v_sub_f32_e32 v21, v21, v50
	s_waitcnt vmcnt(8)
	v_sub_f32_e32 v23, v23, v50
	v_sub_f32_e32 v24, v24, v50
	v_mul_f32_e32 v15, 0x3fb8aa3b, v15
	v_mul_f32_e32 v72, 0x3fb8aa3b, v20
	v_exp_f32_e32 v10, v10
	v_exp_f32_e32 v11, v51
	v_sub_f32_e32 v22, v22, v50
	v_mul_f32_e32 v40, 0x3fb8aa3b, v14
	v_mul_f32_e32 v17, 0x3fb8aa3b, v17
	v_mul_f32_e32 v21, 0x3fb8aa3b, v21
	v_mul_f32_e32 v23, 0x3fb8aa3b, v23
	v_mul_f32_e32 v74, 0x3fb8aa3b, v24
	v_exp_f32_e32 v14, v32
	v_exp_f32_e32 v20, v15
	v_exp_f32_e32 v15, v72
	v_mul_f32_e32 v73, 0x3fb8aa3b, v22
	v_exp_f32_e32 v24, v17
	v_exp_f32_e32 v17, v21
	v_exp_f32_e32 v21, v23
	v_exp_f32_e32 v23, v74
	s_waitcnt vmcnt(6)
	v_and_b32_e32 v75, 0xffff0000, v52
	s_waitcnt vmcnt(5)
	v_and_b32_e32 v74, 0xffff0000, v56
	v_exp_f32_e32 v18, v40
	v_exp_f32_e32 v19, v73
	v_lshlrev_b32_e32 v73, 16, v52
	v_lshlrev_b32_e32 v72, 16, v56
	v_pk_mul_f32 v[12:13], v[12:13], v[74:75]
	v_sub_f32_e32 v25, v25, v50
	v_lshlrev_b32_e32 v77, 16, v53
	v_lshlrev_b32_e32 v76, 16, v57
	v_pk_fma_f32 v[10:11], v[10:11], v[72:73], v[12:13]
	v_mul_f32_e32 v25, 0x3fb8aa3b, v25
	v_exp_f32_e32 v22, v41
	v_and_b32_e32 v53, 0xffff0000, v53
	v_and_b32_e32 v52, 0xffff0000, v57
	v_pk_fma_f32 v[10:11], v[14:15], v[76:77], v[10:11]
	v_exp_f32_e32 v25, v25
	v_lshlrev_b32_e32 v57, 16, v54
	v_lshlrev_b32_e32 v56, 16, v58
	v_pk_fma_f32 v[10:11], v[16:17], v[52:53], v[10:11]
	v_and_b32_e32 v79, 0xffff0000, v54
	v_and_b32_e32 v78, 0xffff0000, v58
	v_pk_fma_f32 v[10:11], v[18:19], v[56:57], v[10:11]
	v_lshlrev_b32_e32 v81, 16, v55
	v_lshlrev_b32_e32 v80, 16, v59
	v_pk_fma_f32 v[10:11], v[20:21], v[78:79], v[10:11]
	v_and_b32_e32 v55, 0xffff0000, v55
	v_and_b32_e32 v54, 0xffff0000, v59
	v_pk_fma_f32 v[10:11], v[22:23], v[80:81], v[10:11]
	v_sub_f32_e32 v18, v27, v50
	v_pk_fma_f32 v[10:11], v[24:25], v[54:55], v[10:11]
	v_mul_f32_e32 v18, 0x3fb8aa3b, v18
	v_add_f32_e32 v10, 0, v10
	v_add_f32_e32 v32, v10, v11
	global_load_dwordx4 v[10:13], v33, s[8:9] offset:144
	global_load_dwordx4 v[14:17], v33, s[8:9] offset:128
	v_exp_f32_e32 v56, v18
	v_sub_f32_e32 v18, v28, v50
	v_mul_f32_e32 v18, 0x3fb8aa3b, v18
	v_exp_f32_e32 v58, v18
	v_sub_f32_e32 v18, v29, v50
	v_mul_f32_e32 v18, 0x3fb8aa3b, v18
	v_sub_f32_e32 v26, v26, v50
	v_exp_f32_e32 v72, v18
	s_waitcnt vmcnt(6)
	v_sub_f32_e32 v18, v60, v50
	v_mul_f32_e32 v26, 0x3fb8aa3b, v26
	v_mul_f32_e32 v18, 0x3fb8aa3b, v18
	v_exp_f32_e32 v40, v26
	v_exp_f32_e32 v60, v18
	v_sub_f32_e32 v18, v61, v50
	s_waitcnt vmcnt(4)
	v_sub_f32_e32 v26, v69, v50
	v_mul_f32_e32 v18, 0x3fb8aa3b, v18
	v_mul_f32_e32 v26, 0x3fb8aa3b, v26
	v_exp_f32_e32 v74, v18
	v_sub_f32_e32 v18, v62, v50
	v_exp_f32_e32 v57, v26
	v_sub_f32_e32 v26, v70, v50
	v_mul_f32_e32 v18, 0x3fb8aa3b, v18
	v_mul_f32_e32 v26, 0x3fb8aa3b, v26
	v_exp_f32_e32 v62, v18
	v_sub_f32_e32 v18, v63, v50
	v_exp_f32_e32 v59, v26
	v_sub_f32_e32 v26, v71, v50
	v_mul_f32_e32 v18, 0x3fb8aa3b, v18
	v_mul_f32_e32 v26, 0x3fb8aa3b, v26
	v_exp_f32_e32 v76, v18
	v_sub_f32_e32 v18, v68, v50
	v_exp_f32_e32 v73, v26
	v_sub_f32_e32 v26, v64, v50
	v_mul_f32_e32 v18, 0x3fb8aa3b, v18
	v_mul_f32_e32 v26, 0x3fb8aa3b, v26
	v_exp_f32_e32 v41, v18
	global_load_dwordx4 v[18:21], v33, s[8:9] offset:176
	global_load_dwordx4 v[22:25], v33, s[8:9] offset:160
	v_exp_f32_e32 v61, v26
	v_sub_f32_e32 v26, v65, v50
	v_mul_f32_e32 v26, 0x3fb8aa3b, v26
	v_exp_f32_e32 v75, v26
	v_sub_f32_e32 v26, v66, v50
	v_mul_f32_e32 v26, 0x3fb8aa3b, v26
	v_exp_f32_e32 v63, v26
	v_sub_f32_e32 v26, v67, v50
	s_waitcnt vmcnt(4)
; DI float bflo(unsigned u) { return __uint_as_float(u << 16); }
; DI float bfhi(unsigned u) { return __uint_as_float(u & 0xffff0000u); }
; DI float fexp(float x) { return __builtin_amdgcn_exp2f(x * LOG2E); }
; DI void phase_m_dc(int wv, const ArgP a) {
;     ...
;         if (tid < 128) { const bf16_t* kr = KVT + (size_t)(h * 128 + tid) * S + t0; const float* gp = GE + (size_t)h * S + t0; float s = 0.f;
; #pragma unroll
;             for (int p = 0; p < 8; ++p) { const u32x4 v = *(const u32x4*)(kr + 8 * p); const f32x4 e0 = *(const f32x4*)(gp + 8 * p), e1 = *(const f32x4*)(gp + 8 * p + 4);
;                 s += bflo(v.x) * fexp(e0[0] - emax) + bfhi(v.x) * fexp(e0[1] - emax) + bflo(v.y) * fexp(e0[2] - emax) + bfhi(v.y) * fexp(e0[3] - emax)
;                    + bflo(v.z) * fexp(e1[0] - emax) + bfhi(v.z) * fexp(e1[1] - emax) + bflo(v.w) * fexp(e1[2] - emax) + bfhi(v.w) * fexp(e1[3] - emax); }
;             NST[(size_t)(c * 4 + h) * 128 + tid] = s; }
	v_and_b32_e32 v67, 0xffff0000, v4
	v_and_b32_e32 v66, 0xffff0000, v0
	v_lshlrev_b32_e32 v65, 16, v4
	v_lshlrev_b32_e32 v64, 16, v0
	v_pk_mul_f32 v[56:57], v[56:57], v[66:67]
	v_mul_f32_e32 v26, 0x3fb8aa3b, v26
	v_pk_fma_f32 v[40:41], v[40:41], v[64:65], v[56:57]
	v_lshlrev_b32_e32 v57, 16, v5
	v_lshlrev_b32_e32 v56, 16, v1
	v_pk_fma_f32 v[40:41], v[58:59], v[56:57], v[40:41]
	v_and_b32_e32 v5, 0xffff0000, v5
	v_and_b32_e32 v4, 0xffff0000, v1
	v_exp_f32_e32 v77, v26
	v_pk_fma_f32 v[0:1], v[72:73], v[4:5], v[40:41]
	v_lshlrev_b32_e32 v5, 16, v6
	v_lshlrev_b32_e32 v4, 16, v2
	v_pk_fma_f32 v[0:1], v[60:61], v[4:5], v[0:1]
	v_and_b32_e32 v5, 0xffff0000, v6
	v_and_b32_e32 v4, 0xffff0000, v2
	v_pk_fma_f32 v[0:1], v[74:75], v[4:5], v[0:1]
	v_lshlrev_b32_e32 v5, 16, v7
	v_lshlrev_b32_e32 v4, 16, v3
	v_pk_fma_f32 v[0:1], v[62:63], v[4:5], v[0:1]
	v_and_b32_e32 v5, 0xffff0000, v7
	v_and_b32_e32 v4, 0xffff0000, v3
	global_load_dwordx4 v[26:29], v[8:9], off offset:64
	global_load_dwordx4 v[52:55], v[8:9], off offset:80
	v_pk_fma_f32 v[40:41], v[76:77], v[4:5], v[0:1]
	global_load_dwordx4 v[0:3], v33, s[8:9] offset:208
	global_load_dwordx4 v[4:7], v33, s[8:9] offset:192
	global_load_dwordx4 v[56:59], v[8:9], off offset:96
	global_load_dwordx4 v[60:63], v[8:9], off offset:112
	v_add_f32_e32 v32, v32, v40
	v_add_f32_e32 v32, v32, v41
	s_waitcnt vmcnt(9)
	v_sub_f32_e32 v13, v13, v50
	s_waitcnt vmcnt(8)
	v_sub_f32_e32 v8, v14, v50
	v_mul_f32_e32 v8, 0x3fb8aa3b, v8
	v_exp_f32_e32 v40, v8
	v_sub_f32_e32 v8, v15, v50
	v_mul_f32_e32 v8, 0x3fb8aa3b, v8
	v_exp_f32_e32 v64, v8
	v_sub_f32_e32 v8, v16, v50
	v_mul_f32_e32 v8, 0x3fb8aa3b, v8
	v_exp_f32_e32 v66, v8
	v_sub_f32_e32 v8, v17, v50
	v_mul_f32_e32 v8, 0x3fb8aa3b, v8
	v_exp_f32_e32 v68, v8
	v_sub_f32_e32 v8, v10, v50
	v_mul_f32_e32 v8, 0x3fb8aa3b, v8
	v_exp_f32_e32 v70, v8
	v_sub_f32_e32 v8, v11, v50
	v_mul_f32_e32 v8, 0x3fb8aa3b, v8
	v_exp_f32_e32 v72, v8
	global_load_dwordx4 v[8:11], v33, s[8:9] offset:240
	global_load_dwordx4 v[14:17], v33, s[8:9] offset:224
	v_mul_f32_e32 v13, 0x3fb8aa3b, v13
	v_exp_f32_e32 v74, v13
	v_sub_f32_e32 v12, v12, v50
	v_mul_f32_e32 v12, 0x3fb8aa3b, v12
	v_exp_f32_e32 v12, v12
	s_lshl_b64 s[8:9], s[2:3], 9
	s_waitcnt vmcnt(8)
	v_sub_f32_e32 v13, v22, v50
	v_mul_f32_e32 v13, 0x3fb8aa3b, v13
	v_exp_f32_e32 v41, v13
	v_sub_f32_e32 v13, v23, v50
	v_mul_f32_e32 v13, 0x3fb8aa3b, v13
	v_exp_f32_e32 v65, v13
	v_sub_f32_e32 v13, v24, v50
	v_mul_f32_e32 v13, 0x3fb8aa3b, v13
	v_exp_f32_e32 v67, v13
	v_sub_f32_e32 v13, v25, v50
	v_mul_f32_e32 v13, 0x3fb8aa3b, v13
	v_exp_f32_e32 v69, v13
	v_sub_f32_e32 v13, v18, v50
	v_mul_f32_e32 v13, 0x3fb8aa3b, v13
	v_exp_f32_e32 v71, v13
	v_sub_f32_e32 v13, v19, v50
	v_mul_f32_e32 v13, 0x3fb8aa3b, v13
	v_sub_f32_e32 v18, v21, v50
	v_exp_f32_e32 v73, v13
	v_sub_f32_e32 v13, v20, v50
	v_mul_f32_e32 v18, 0x3fb8aa3b, v18
	v_exp_f32_e32 v75, v18
	v_mul_f32_e32 v13, 0x3fb8aa3b, v13
	v_exp_f32_e32 v13, v13
	s_waitcnt vmcnt(7)
	v_and_b32_e32 v20, 0xffff0000, v26
	s_waitcnt vmcnt(6)
	v_and_b32_e32 v21, 0xffff0000, v52
	v_lshlrev_b32_e32 v19, 16, v52
	v_lshlrev_b32_e32 v18, 16, v26
	v_pk_mul_f32 v[20:21], v[64:65], v[20:21]
	s_waitcnt vmcnt(5)
	v_sub_f32_e32 v1, v1, v50
	v_pk_fma_f32 v[18:19], v[40:41], v[18:19], v[20:21]
	v_lshlrev_b32_e32 v21, 16, v53
	v_lshlrev_b32_e32 v20, 16, v27
	v_pk_fma_f32 v[18:19], v[66:67], v[20:21], v[18:19]
	v_and_b32_e32 v21, 0xffff0000, v53
	v_and_b32_e32 v20, 0xffff0000, v27
	v_pk_fma_f32 v[18:19], v[68:69], v[20:21], v[18:19]
	v_lshlrev_b32_e32 v21, 16, v54
	v_lshlrev_b32_e32 v20, 16, v28
	v_pk_fma_f32 v[18:19], v[70:71], v[20:21], v[18:19]
	v_and_b32_e32 v21, 0xffff0000, v54
	v_and_b32_e32 v20, 0xffff0000, v28
	v_pk_fma_f32 v[18:19], v[72:73], v[20:21], v[18:19]
	v_lshlrev_b32_e32 v21, 16, v55
	v_lshlrev_b32_e32 v20, 16, v29
	v_pk_fma_f32 v[12:13], v[12:13], v[20:21], v[18:19]
	v_and_b32_e32 v19, 0xffff0000, v55
	v_and_b32_e32 v18, 0xffff0000, v29
	v_mul_f32_e32 v1, 0x3fb8aa3b, v1
	v_pk_fma_f32 v[12:13], v[74:75], v[18:19], v[12:13]
	s_waitcnt vmcnt(4)
	v_sub_f32_e32 v5, v5, v50
	v_exp_f32_e32 v20, v1
	v_sub_f32_e32 v1, v2, v50
	v_add_f32_e32 v12, v32, v12
	v_mul_f32_e32 v5, 0x3fb8aa3b, v5
	v_mul_f32_e32 v1, 0x3fb8aa3b, v1
	v_add_f32_e32 v24, v12, v13
	v_exp_f32_e32 v12, v5
	v_sub_f32_e32 v5, v6, v50
	v_exp_f32_e32 v2, v1
	v_sub_f32_e32 v1, v3, v50
	v_mul_f32_e32 v5, 0x3fb8aa3b, v5
	v_mul_f32_e32 v1, 0x3fb8aa3b, v1
	v_exp_f32_e32 v6, v5
	v_sub_f32_e32 v5, v7, v50
	v_exp_f32_e32 v22, v1
	s_waitcnt vmcnt(0)
	v_sub_f32_e32 v1, v14, v50
	v_mul_f32_e32 v5, 0x3fb8aa3b, v5
	v_mul_f32_e32 v1, 0x3fb8aa3b, v1
	v_exp_f32_e32 v18, v5
	v_exp_f32_e32 v5, v1
	v_sub_f32_e32 v1, v15, v50
	v_mul_f32_e32 v1, 0x3fb8aa3b, v1
	v_exp_f32_e32 v13, v1
	v_sub_f32_e32 v1, v16, v50
	v_sub_f32_e32 v4, v4, v50
	v_mul_f32_e32 v1, 0x3fb8aa3b, v1
	v_mul_f32_e32 v4, 0x3fb8aa3b, v4
	v_exp_f32_e32 v7, v1
	v_sub_f32_e32 v1, v17, v50
	v_exp_f32_e32 v4, v4
	v_mul_f32_e32 v1, 0x3fb8aa3b, v1
	v_sub_f32_e32 v3, v9, v50
	v_sub_f32_e32 v0, v0, v50
	v_exp_f32_e32 v19, v1
	v_sub_f32_e32 v1, v8, v50
	v_mul_f32_e32 v3, 0x3fb8aa3b, v3
	v_sub_f32_e32 v8, v11, v50
	v_mul_f32_e32 v0, 0x3fb8aa3b, v0
	v_mul_f32_e32 v1, 0x3fb8aa3b, v1
	v_exp_f32_e32 v21, v3
	v_sub_f32_e32 v3, v10, v50
	v_mul_f32_e32 v8, 0x3fb8aa3b, v8
	v_and_b32_e32 v11, 0xffff0000, v60
	v_and_b32_e32 v10, 0xffff0000, v56
	v_exp_f32_e32 v0, v0
	v_exp_f32_e32 v1, v1
	v_exp_f32_e32 v23, v8
	v_lshlrev_b32_e32 v9, 16, v60
	v_lshlrev_b32_e32 v8, 16, v56
	v_pk_mul_f32 v[10:11], v[12:13], v[10:11]
	v_mul_f32_e32 v3, 0x3fb8aa3b, v3
	v_pk_fma_f32 v[4:5], v[4:5], v[8:9], v[10:11]
	v_lshlrev_b32_e32 v9, 16, v61
	v_lshlrev_b32_e32 v8, 16, v57
	v_exp_f32_e32 v3, v3
	v_pk_fma_f32 v[4:5], v[6:7], v[8:9], v[4:5]
	v_and_b32_e32 v7, 0xffff0000, v61
	v_and_b32_e32 v6, 0xffff0000, v57
	v_pk_fma_f32 v[4:5], v[18:19], v[6:7], v[4:5]
	v_lshlrev_b32_e32 v7, 16, v62
	v_lshlrev_b32_e32 v6, 16, v58
	v_pk_fma_f32 v[0:1], v[0:1], v[6:7], v[4:5]
	v_and_b32_e32 v5, 0xffff0000, v62
	v_and_b32_e32 v4, 0xffff0000, v58
	v_pk_fma_f32 v[0:1], v[20:21], v[4:5], v[0:1]
	v_lshlrev_b32_e32 v5, 16, v63
	v_lshlrev_b32_e32 v4, 16, v59
	v_pk_fma_f32 v[0:1], v[2:3], v[4:5], v[0:1]
	v_and_b32_e32 v3, 0xffff0000, v63
	v_and_b32_e32 v2, 0xffff0000, v59
	v_pk_fma_f32 v[0:1], v[22:23], v[2:3], v[0:1]
	s_nop 0
	v_add_f32_e32 v0, v24, v0
	v_add_f32_e32 v2, v0, v1
	v_lshl_add_u64 v[0:1], v[34:35], 0, s[8:9]
	global_store_dword v[0:1], v2, off
	s_branch .LBB0_1462
